# diff-attention steady loop rewritten by hand: rolling LDS fragment prefetch 6 MFMA slots ahead, even/odd bodies without S=N copies
# speedup vs baseline: 1.0198x; 1.0188x over previous
; #define ATT_LAS __attribute__((address_space(3)))
; #define SB0() __builtin_amdgcn_sched_barrier(0)
; __device__ __forceinline__ void hs_fast(f32x16& S, f32x16 (&O)[4], bf16x8 (&pf)[2], float& lsum, const bf16x8 (&qf)[4], const ATT_LAS unsigned char* ka, const ATT_LAS unsigned char* va) {
;     bf16x8 kf[4], vf[8]; f32x16 N; float acc;
;     const f32x16 Z = {0.f, 0.f, 0.f, 0.f, 0.f, 0.f, 0.f, 0.f, 0.f, 0.f, 0.f, 0.f, 0.f, 0.f, 0.f, 0.f};
;     kf[0] = LDF(ka); kf[1] = LDF(ka + 32); kf[2] = LDF(ka + 64); kf[3] = LDF(ka + 96);
;     vf[0] = LDF(va); vf[1] = LDF(va + 32 * VPITCH); vf[2] = LDF(va + 64 * VPITCH); vf[3] = LDF(va + 96 * VPITCH);
;     SB0();
;     N = MFMA32(kf[0], qf[0], Z);          S[0] = EX2(S[0]); S[1] = EX2(S[1]);
;     SB0();
;     O[0] = MFMA32(vf[0], pf[0], O[0]);    S[2] = EX2(S[2]); S[3] = EX2(S[3]); acc = S[0] + S[1];
;     SB0();
;     N = MFMA32(kf[1], qf[1], N);          S[4] = EX2(S[4]); S[5] = EX2(S[5]); acc += S[2]; acc += S[3];
;     SB0();
;     O[1] = MFMA32(vf[1], pf[0], O[1]);    S[6] = EX2(S[6]); S[7] = EX2(S[7]); acc += S[4]; acc += S[5];
;     SB0();
;     N = MFMA32(kf[2], qf[2], N);          S[8] = EX2(S[8]); S[9] = EX2(S[9]); acc += S[6]; acc += S[7];
;     vf[4] = LDF(va + 32); vf[5] = LDF(va + 32 * VPITCH + 32);
;     SB0();
;     O[2] = MFMA32(vf[2], pf[0], O[2]);    S[10] = EX2(S[10]); S[11] = EX2(S[11]); acc += S[8]; acc += S[9];
;     vf[6] = LDF(va + 64 * VPITCH + 32); vf[7] = LDF(va + 96 * VPITCH + 32);
;     SB0();
;     N = MFMA32(kf[3], qf[3], N);          S[12] = EX2(S[12]); S[13] = EX2(S[13]); acc += S[10]; acc += S[11];
;     SB0();
;     O[3] = MFMA32(vf[3], pf[0], O[3]);    S[14] = EX2(S[14]); S[15] = EX2(S[15]); acc += S[12]; acc += S[13];
;     SB0();
;     u32x4 w0, w1;
;     O[0] = MFMA32(vf[4], pf[1], O[0]);    w0.x = cvt_pk_bf16(S[0], S[1]); w0.y = cvt_pk_bf16(S[2], S[3]); acc += S[14]; acc += S[15];
;     SB0();
;     O[1] = MFMA32(vf[5], pf[1], O[1]);    w0.z = cvt_pk_bf16(S[4], S[5]); w0.w = cvt_pk_bf16(S[6], S[7]);
;     SB0();
;     O[2] = MFMA32(vf[6], pf[1], O[2]);    w1.x = cvt_pk_bf16(S[8], S[9]); w1.y = cvt_pk_bf16(S[10], S[11]);
;     SB0();
;     O[3] = MFMA32(vf[7], pf[1], O[3]);    w1.z = cvt_pk_bf16(S[12], S[13]); w1.w = cvt_pk_bf16(S[14], S[15]);
;     SB0();
;     lsum += acc; pf[0] = __builtin_bit_cast(bf16x8, w0); pf[1] = __builtin_bit_cast(bf16x8, w1); S = N;
; }
.LBB0_535:
	s_lshl_b32 s22, s46, 1
	s_add_i32 s23, s22, 3
	s_cmp_lt_u32 s42, 3
	s_cbranch_scc1 .LBB0_542
	v_mov_b32_e32 v16, 0
	s_add_i32 s24, s45, s39
	s_movk_i32 s25, 0x1c0
	s_mov_b32 s46, 0
	s_movk_i32 s47, 0x60
	v_mov_b32_e32 v17, v16
	v_mov_b32_e32 v18, v16
	v_mov_b32_e32 v19, v16
	v_mov_b32_e32 v20, v16
	v_mov_b32_e32 v21, v16
	v_mov_b32_e32 v22, v16
	v_mov_b32_e32 v23, v16
	v_mov_b32_e32 v24, v16
	v_mov_b32_e32 v25, v16
	v_mov_b32_e32 v26, v16
	v_mov_b32_e32 v27, v16
	v_mov_b32_e32 v28, v16
	v_mov_b32_e32 v29, v16
	v_mov_b32_e32 v30, v16
	v_mov_b32_e32 v31, v16
	v_mov_b32_e32 v32, v16
	v_mov_b32_e32 v33, v16
	v_mov_b32_e32 v34, v16
	v_mov_b32_e32 v35, v16
	v_mov_b32_e32 v36, v16
	v_mov_b32_e32 v37, v16
	v_mov_b32_e32 v38, v16
	v_mov_b32_e32 v39, v16
	v_mov_b32_e32 v40, v16
	v_mov_b32_e32 v41, v16
	v_mov_b32_e32 v42, v16
	v_mov_b32_e32 v43, v16
	v_mov_b32_e32 v44, v16
	v_mov_b32_e32 v45, v16
	v_mov_b32_e32 v46, v16
	v_mov_b32_e32 v47, v16
	v_mov_b32_e32 v48, v16
	v_mov_b32_e32 v49, v16
	v_mov_b32_e32 v50, v16
	v_mov_b32_e32 v51, v16
	v_mov_b32_e32 v52, v16
	v_mov_b32_e32 v53, v16
	v_mov_b32_e32 v54, v16
	v_mov_b32_e32 v55, v16
	v_mov_b32_e32 v56, v16
	v_mov_b32_e32 v57, v16
	v_mov_b32_e32 v58, v16
	v_mov_b32_e32 v59, v16
	v_mov_b32_e32 v60, v16
	v_mov_b32_e32 v61, v16
	v_mov_b32_e32 v62, v16
	v_mov_b32_e32 v63, v16
	v_mov_b32_e32 v64, v16
	v_mov_b32_e32 v65, v16
	v_mov_b32_e32 v66, v16
	v_mov_b32_e32 v67, v16
	v_mov_b32_e32 v68, v16
	v_mov_b32_e32 v69, v16
	v_mov_b32_e32 v70, v16
	v_mov_b32_e32 v71, v16
	v_mov_b32_e32 v72, v16
	v_mov_b32_e32 v73, v16
	v_mov_b32_e32 v74, v16
	v_mov_b32_e32 v75, v16
	v_mov_b32_e32 v76, v16
	v_mov_b32_e32 v77, v16
	v_mov_b32_e32 v78, v16
	v_mov_b32_e32 v79, v16
	s_mov_b32 s98, 0
	s_mov_b32 s99, 0x8c00
	s_mov_b32 s100, 0x11800
	s_mov_b32 s47, 4
	v_mov_b32_e32 v150, v148
	v_mov_b32_e32 v151, v149
	v_add_u32_e32 v14, 0x8c00, v163
	v_mov_b32_e32 v1, v196
	ds_read_b128 v[218:221], v14 offset:8704
	ds_read_b128 v[222:225], v1 offset:17472
	ds_read_b128 v[226:229], v14 offset:8736
	ds_read_b128 v[230:233], v1 offset:22080
	ds_read_b128 v[234:237], v14 offset:8768
	ds_read_b128 v[2:5], v1 offset:26688
	s_waitcnt lgkmcnt(0)
.Lfa_even:
	v_mov_b32_e32 v15, v1
	v_add_u32_e32 v1, s99, v196
	s_waitcnt lgkmcnt(9)
	v_mfma_f32_32x32x16_bf16 v[96:111], v[218:221], v[112:115], 0
	v_exp_f32_e32 v80, v80
	v_exp_f32_e32 v81, v81
	ds_read_b128 v[218:221], v14 offset:8800
	v_add_f32_e32 v244, v80, v81
	s_waitcnt lgkmcnt(8)
	v_mfma_f32_32x32x16_bf16 v[64:79], v[222:225], v[144:147], v[64:79]
	v_exp_f32_e32 v82, v82
	v_exp_f32_e32 v83, v83
	ds_read_b128 v[222:225], v15 offset:31296
	v_add_f32_e32 v245, v82, v83
	s_waitcnt lgkmcnt(7)
	v_mfma_f32_32x32x16_bf16 v[96:111], v[226:229], v[116:119], v[96:111]
	v_exp_f32_e32 v84, v84
	v_exp_f32_e32 v85, v85
	ds_read_b128 v[226:229], v15 offset:17504
	v_add_f32_e32 v244, v244, v84
	v_add_f32_e32 v245, v245, v85
	s_waitcnt lgkmcnt(6)
	v_mfma_f32_32x32x16_bf16 v[48:63], v[230:233], v[144:147], v[48:63]
	v_exp_f32_e32 v86, v86
	v_exp_f32_e32 v87, v87
	ds_read_b128 v[230:233], v15 offset:22112
	v_add_f32_e32 v244, v244, v86
	v_add_f32_e32 v245, v245, v87
	s_waitcnt lgkmcnt(5)
	v_mfma_f32_32x32x16_bf16 v[96:111], v[234:237], v[120:123], v[96:111]
	v_exp_f32_e32 v88, v88
	v_exp_f32_e32 v89, v89
	ds_read_b128 v[234:237], v15 offset:26720
	v_add_f32_e32 v244, v244, v88
	v_add_f32_e32 v245, v245, v89
	s_waitcnt lgkmcnt(5)
	v_mfma_f32_32x32x16_bf16 v[32:47], v[2:5], v[144:147], v[32:47]
	v_exp_f32_e32 v90, v90
	v_exp_f32_e32 v91, v91
	ds_read_b128 v[2:5], v15 offset:31328
	v_add_f32_e32 v244, v244, v90
	v_add_f32_e32 v245, v245, v91
	s_waitcnt lgkmcnt(5)
	v_mfma_f32_32x32x16_bf16 v[96:111], v[218:221], v[124:127], v[96:111]
	v_exp_f32_e32 v92, v92
	v_exp_f32_e32 v93, v93
	ds_read_b128 v[218:221], v1 offset:17408
	v_add_f32_e32 v244, v244, v92
	v_add_f32_e32 v245, v245, v93
	s_waitcnt lgkmcnt(5)
	v_mfma_f32_32x32x16_bf16 v[16:31], v[222:225], v[144:147], v[16:31]
	v_exp_f32_e32 v94, v94
	v_exp_f32_e32 v95, v95
	ds_read_b128 v[222:225], v1 offset:22016
	v_add_f32_e32 v244, v244, v94
	v_add_f32_e32 v245, v245, v95
	s_waitcnt lgkmcnt(5)
	v_mfma_f32_32x32x16_bf16 v[64:79], v[226:229], v[150:153], v[64:79]
	v_add_f32_e32 v161, v161, v244
	v_cvt_pk_bf16_f32 v6, v80, v81
	v_cvt_pk_bf16_f32 v7, v82, v83
	ds_read_b128 v[226:229], v1 offset:26624
	s_waitcnt lgkmcnt(5)
	v_mfma_f32_32x32x16_bf16 v[48:63], v[230:233], v[150:153], v[48:63]
	v_add_f32_e32 v161, v161, v245
	v_cvt_pk_bf16_f32 v8, v84, v85
	v_cvt_pk_bf16_f32 v9, v86, v87
	ds_read_b128 v[230:233], v1 offset:31232
	s_waitcnt lgkmcnt(5)
	v_mfma_f32_32x32x16_bf16 v[32:47], v[234:237], v[150:153], v[32:47]
	v_cvt_pk_bf16_f32 v10, v88, v89
	v_cvt_pk_bf16_f32 v11, v90, v91
	s_waitcnt lgkmcnt(4)
	v_mfma_f32_32x32x16_bf16 v[16:31], v[2:5], v[150:153], v[16:31]
	v_cvt_pk_bf16_f32 v12, v92, v93
	v_cvt_pk_bf16_f32 v13, v94, v95
	ds_read_b128 v[2:5], v1 offset:17440
	s_add_i32 s46, s46, 1
	s_cmp_eq_u32 s46, s24
	s_cbranch_scc1 .Lfa_exit_even
; #define ATT_LAS __attribute__((address_space(3)))
; #define SB0() __builtin_amdgcn_sched_barrier(0)
; __device__ __forceinline__ void hs_fast(f32x16& S, f32x16 (&O)[4], bf16x8 (&pf)[2], float& lsum, const bf16x8 (&qf)[4], const ATT_LAS unsigned char* ka, const ATT_LAS unsigned char* va) {
;     bf16x8 kf[4], vf[8]; f32x16 N; float acc;
;     const f32x16 Z = {0.f, 0.f, 0.f, 0.f, 0.f, 0.f, 0.f, 0.f, 0.f, 0.f, 0.f, 0.f, 0.f, 0.f, 0.f, 0.f};
;     kf[0] = LDF(ka); kf[1] = LDF(ka + 32); kf[2] = LDF(ka + 64); kf[3] = LDF(ka + 96);
;     vf[0] = LDF(va); vf[1] = LDF(va + 32 * VPITCH); vf[2] = LDF(va + 64 * VPITCH); vf[3] = LDF(va + 96 * VPITCH);
;     SB0();
;     N = MFMA32(kf[0], qf[0], Z);          S[0] = EX2(S[0]); S[1] = EX2(S[1]);
;     SB0();
;     O[0] = MFMA32(vf[0], pf[0], O[0]);    S[2] = EX2(S[2]); S[3] = EX2(S[3]); acc = S[0] + S[1];
;     SB0();
;     N = MFMA32(kf[1], qf[1], N);          S[4] = EX2(S[4]); S[5] = EX2(S[5]); acc += S[2]; acc += S[3];
;     SB0();
;     O[1] = MFMA32(vf[1], pf[0], O[1]);    S[6] = EX2(S[6]); S[7] = EX2(S[7]); acc += S[4]; acc += S[5];
;     SB0();
;     N = MFMA32(kf[2], qf[2], N);          S[8] = EX2(S[8]); S[9] = EX2(S[9]); acc += S[6]; acc += S[7];
;     vf[4] = LDF(va + 32); vf[5] = LDF(va + 32 * VPITCH + 32);
;     SB0();
;     O[2] = MFMA32(vf[2], pf[0], O[2]);    S[10] = EX2(S[10]); S[11] = EX2(S[11]); acc += S[8]; acc += S[9];
;     vf[6] = LDF(va + 64 * VPITCH + 32); vf[7] = LDF(va + 96 * VPITCH + 32);
;     SB0();
;     N = MFMA32(kf[3], qf[3], N);          S[12] = EX2(S[12]); S[13] = EX2(S[13]); acc += S[10]; acc += S[11];
;     SB0();
;     O[3] = MFMA32(vf[3], pf[0], O[3]);    S[14] = EX2(S[14]); S[15] = EX2(S[15]); acc += S[12]; acc += S[13];
;     SB0();
;     u32x4 w0, w1;
;     O[0] = MFMA32(vf[4], pf[1], O[0]);    w0.x = cvt_pk_bf16(S[0], S[1]); w0.y = cvt_pk_bf16(S[2], S[3]); acc += S[14]; acc += S[15];
;     SB0();
;     O[1] = MFMA32(vf[5], pf[1], O[1]);    w0.z = cvt_pk_bf16(S[4], S[5]); w0.w = cvt_pk_bf16(S[6], S[7]);
;     SB0();
;     O[2] = MFMA32(vf[6], pf[1], O[2]);    w1.x = cvt_pk_bf16(S[8], S[9]); w1.y = cvt_pk_bf16(S[10], S[11]);
;     SB0();
;     O[3] = MFMA32(vf[7], pf[1], O[3]);    w1.z = cvt_pk_bf16(S[12], S[13]); w1.w = cvt_pk_bf16(S[14], S[15]);
;     SB0();
;     lsum += acc; pf[0] = __builtin_bit_cast(bf16x8, w0); pf[1] = __builtin_bit_cast(bf16x8, w1); S = N;
; }
	s_barrier
	v_add_u32_e32 v14, s100, v163
	ds_read_b128 v[234:237], v14
	v_add_u32_e32 v246, s98, v193
	v_add_u32_e32 v247, s98, v194
	s_waitcnt lgkmcnt(5)
	v_mfma_f32_32x32x16_bf16 v[64:79], v[218:221], v[6:9], v[64:79]
	v_exp_f32_e32 v96, v96
	v_exp_f32_e32 v97, v97
	ds_read_b128 v[218:221], v14 offset:32
	v_add_f32_e32 v244, v96, v97
	s_waitcnt lgkmcnt(5)
	v_mfma_f32_32x32x16_bf16 v[48:63], v[222:225], v[6:9], v[48:63]
	v_exp_f32_e32 v98, v98
	v_exp_f32_e32 v99, v99
	ds_read_b128 v[222:225], v1 offset:22048
	v_add_f32_e32 v245, v98, v99
	s_waitcnt lgkmcnt(5)
	v_mfma_f32_32x32x16_bf16 v[32:47], v[226:229], v[6:9], v[32:47]
	v_exp_f32_e32 v100, v100
	v_exp_f32_e32 v101, v101
	ds_read_b128 v[226:229], v14 offset:64
	v_add_f32_e32 v244, v244, v100
	v_add_f32_e32 v245, v245, v101
	s_waitcnt lgkmcnt(5)
	v_mfma_f32_32x32x16_bf16 v[16:31], v[230:233], v[6:9], v[16:31]
	v_exp_f32_e32 v102, v102
	v_exp_f32_e32 v103, v103
	ds_read_b128 v[230:233], v1 offset:26656
	v_add_f32_e32 v244, v244, v102
	v_add_f32_e32 v245, v245, v103
	s_waitcnt lgkmcnt(4)
	v_mfma_f32_32x32x16_bf16 v[80:95], v[234:237], v[112:115], 0
	v_exp_f32_e32 v104, v104
	v_exp_f32_e32 v105, v105
	ds_read_b128 v[234:237], v14 offset:96
	v_add_f32_e32 v244, v244, v104
	v_add_f32_e32 v245, v245, v105
	s_waitcnt lgkmcnt(5)
	v_mfma_f32_32x32x16_bf16 v[64:79], v[2:5], v[10:13], v[64:79]
	v_exp_f32_e32 v106, v106
	v_exp_f32_e32 v107, v107
	ds_read_b128 v[2:5], v1 offset:31264
	v_add_f32_e32 v244, v244, v106
	v_add_f32_e32 v245, v245, v107
	s_waitcnt lgkmcnt(5)
	v_mfma_f32_32x32x16_bf16 v[80:95], v[218:221], v[116:119], v[80:95]
	v_exp_f32_e32 v108, v108
	v_exp_f32_e32 v109, v109
	ds_read_b128 v[218:221], v14 offset:8704
	v_add_f32_e32 v244, v244, v108
	v_add_f32_e32 v245, v245, v109
	s_waitcnt vmcnt(0)
	ds_write_b128 v246, v[128:131]
	s_waitcnt lgkmcnt(6)
	v_mfma_f32_32x32x16_bf16 v[48:63], v[222:225], v[10:13], v[48:63]
	v_exp_f32_e32 v110, v110
	v_exp_f32_e32 v111, v111
	ds_read_b128 v[222:225], v1 offset:17472
	v_add_f32_e32 v244, v244, v110
	v_add_f32_e32 v245, v245, v111
	ds_write_b128 v247, v[132:135] offset:17408
	s_waitcnt lgkmcnt(7)
	v_mfma_f32_32x32x16_bf16 v[80:95], v[226:229], v[120:123], v[80:95]
	v_add_f32_e32 v161, v161, v244
	v_cvt_pk_bf16_f32 v144, v96, v97
	v_cvt_pk_bf16_f32 v145, v98, v99
	ds_read_b128 v[226:229], v14 offset:8736
	ds_write_b128 v246, v[136:139] offset:8704
	s_waitcnt lgkmcnt(8)
	v_mfma_f32_32x32x16_bf16 v[32:47], v[230:233], v[10:13], v[32:47]
	v_add_f32_e32 v161, v161, v245
	v_cvt_pk_bf16_f32 v146, v100, v101
	v_cvt_pk_bf16_f32 v147, v102, v103
	ds_read_b128 v[230:233], v1 offset:22080
	ds_write_b128 v247, v[140:143] offset:26624
	s_waitcnt lgkmcnt(9)
	v_mfma_f32_32x32x16_bf16 v[80:95], v[234:237], v[124:127], v[80:95]
	v_cvt_pk_bf16_f32 v150, v104, v105
	v_cvt_pk_bf16_f32 v151, v106, v107
	ds_read_b128 v[234:237], v14 offset:8768
	s_cmp_ge_u32 s47, s23
	s_cbranch_scc1 .Lfa_noload
	s_lshl_b32 s48, s47, 17
	s_mov_b32 s49, 0
	v_lshl_add_u64 v[240:241], v[182:183], 0, s[48:49]
	s_lshl_b32 s4, s47, 7
	s_add_u32 s48, s48, 0x10000
	global_load_dwordx4 v[128:131], v[240:241], off
	v_lshl_add_u64 v[242:243], v[182:183], 0, s[48:49]
	s_mov_b32 s48, s4
	v_lshl_add_u64 v[240:241], v[184:185], 0, s[48:49]
	s_add_u32 s48, s48, 0x208000
	global_load_dwordx4 v[132:135], v[240:241], off
	global_load_dwordx4 v[136:139], v[242:243], off
	v_lshl_add_u64 v[240:241], v[184:185], 0, s[48:49]
	s_nop 0
	global_load_dwordx4 v[140:143], v[240:241], off
.Lfa_noload:
	s_waitcnt lgkmcnt(9)
	v_mfma_f32_32x32x16_bf16 v[16:31], v[2:5], v[10:13], v[16:31]
	v_cvt_pk_bf16_f32 v152, v108, v109
	v_cvt_pk_bf16_f32 v153, v110, v111
	ds_read_b128 v[2:5], v1 offset:26688
	s_mov_b32 s101, s98
	s_mov_b32 s98, s99
	s_mov_b32 s99, s100
	s_mov_b32 s100, s101
	s_add_i32 s47, s47, 1
	s_add_i32 s46, s46, 1
	s_cmp_eq_u32 s46, s24
	s_cbranch_scc0 .Lfa_even
	s_waitcnt lgkmcnt(0)
	v_mov_b32_e32 v148, v150
	v_mov_b32_e32 v149, v151
	s_mov_b32 s4, s42
	s_lshl_b32 s24, s23, 1
	s_cmp_gt_u32 s4, s24
	s_cbranch_scc1 .LBB0_556
	s_branch .LBB0_544
.Lfa_exit_even:
	s_waitcnt lgkmcnt(0)
	v_mov_b32_e32 v144, v6
	v_mov_b32_e32 v145, v7
	v_mov_b32_e32 v146, v8
	v_mov_b32_e32 v147, v9
	v_mov_b32_e32 v148, v10
	v_mov_b32_e32 v149, v11
	v_mov_b32_e32 v152, v12
	v_mov_b32_e32 v153, v13
	s_branch .LBB0_543

; __global__ void __launch_bounds__(NWAVES * 64, 2) fwd(Params P) {
	.amdhsa_kernel _Z3fwd6Params
		.amdhsa_group_segment_fixed_size 0
		.amdhsa_private_segment_fixed_size 0
		.amdhsa_kernarg_size 536
		.amdhsa_user_sgpr_count 2
		.amdhsa_user_sgpr_dispatch_ptr 0
		.amdhsa_user_sgpr_queue_ptr 0
		.amdhsa_user_sgpr_kernarg_segment_ptr 1
		.amdhsa_user_sgpr_dispatch_id 0
		.amdhsa_user_sgpr_kernarg_preload_length 0
		.amdhsa_user_sgpr_kernarg_preload_offset 0
		.amdhsa_user_sgpr_private_segment_size 0
		.amdhsa_uses_dynamic_stack 0
		.amdhsa_enable_private_segment 0
		.amdhsa_system_sgpr_workgroup_id_x 1
		.amdhsa_system_sgpr_workgroup_id_y 0
		.amdhsa_system_sgpr_workgroup_id_z 0
		.amdhsa_system_sgpr_workgroup_info 0
		.amdhsa_system_vgpr_workitem_id 2
		.amdhsa_next_free_vgpr 248
		.amdhsa_next_free_sgpr 102
		.amdhsa_accum_offset 248
		.amdhsa_reserve_vcc 1
		.amdhsa_float_round_mode_32 0
		.amdhsa_float_round_mode_16_64 0
		.amdhsa_float_denorm_mode_32 3
		.amdhsa_float_denorm_mode_16_64 3
		.amdhsa_dx10_clamp 1
		.amdhsa_ieee_mode 1
		.amdhsa_fp16_overflow 0
		.amdhsa_tg_split 0
		.amdhsa_exception_fp_ieee_invalid_op 0
		.amdhsa_exception_fp_denorm_src 0
		.amdhsa_exception_fp_ieee_div_zero 0
		.amdhsa_exception_fp_ieee_overflow 0
		.amdhsa_exception_fp_ieee_underflow 0
		.amdhsa_exception_fp_ieee_inexact 0
		.amdhsa_exception_int_div_zero 0
	.end_amdhsa_kernel

; __global__ void __launch_bounds__(NWAVES * 64, 2) fwd(Params P) {
amdhsa.kernels:
  - .agpr_count:     0
    .args:
      - .offset:         0
        .size:           280
        .value_kind:     by_value
      - .offset:         280
        .size:           4
        .value_kind:     hidden_block_count_x
      - .offset:         284
        .size:           4
        .value_kind:     hidden_block_count_y
      - .offset:         288
        .size:           4
        .value_kind:     hidden_block_count_z
      - .offset:         292
        .size:           2
        .value_kind:     hidden_group_size_x
      - .offset:         294
        .size:           2
        .value_kind:     hidden_group_size_y
      - .offset:         296
        .size:           2
        .value_kind:     hidden_group_size_z
      - .offset:         298
        .size:           2
        .value_kind:     hidden_remainder_x
      - .offset:         300
        .size:           2
        .value_kind:     hidden_remainder_y
      - .offset:         302
        .size:           2
        .value_kind:     hidden_remainder_z
      - .offset:         320
        .size:           8
        .value_kind:     hidden_global_offset_x
      - .offset:         328
        .size:           8
        .value_kind:     hidden_global_offset_y
      - .offset:         336
        .size:           8
        .value_kind:     hidden_global_offset_z
      - .offset:         344
        .size:           2
        .value_kind:     hidden_grid_dims
      - .offset:         368
        .size:           8
        .value_kind:     hidden_multigrid_sync_arg
      - .offset:         400
        .size:           4
        .value_kind:     hidden_dynamic_lds_size
    .group_segment_fixed_size: 0
    .kernarg_segment_align: 8
    .kernarg_segment_size: 536
    .language:       OpenCL C
    .language_version:
      - 2
      - 0
    .max_flat_workgroup_size: 512
    .name:           _Z3fwd6Params
    .private_segment_fixed_size: 0
    .sgpr_count:     108
    .sgpr_spill_count: 28
    .symbol:         _Z3fwd6Params.kd
    .uniform_work_group_size: 1
    .uses_dynamic_stack: false
    .vgpr_count:     248
    .vgpr_spill_count: 0
    .wavefront_size: 64
